# strategy 7.5: v_pk_fma_f32 / v_pk_mul_f32 in both attention loops split into scalar pairs (on top of v4)
# speedup vs baseline: 1.0067x; 1.0067x over previous
; #define LAS __attribute__((address_space(3)))
; #define FA_MFMA(a, b, c) __builtin_amdgcn_mfma_f32_32x32x16_bf16((a), (b), (c), 0, 0, 0)
; #define FA_SB() __builtin_amdgcn_sched_barrier(0)
; template <int DQK, bool HAS_LSE>
; __device__ __forceinline__ void unit(LAS unsigned char* lds, const Desc& d) {
;     ...
;         const bool active = (64 * t <= qw + 31) && (64 * t + 63 >= qw - d.W);
;         if (active) {
;             const unsigned vba = (unsigned)(unsigned long)(lds + vfo + slot * VT);
;             f32x16 p0, p1;
; #pragma unroll
;             for (int i = 0; i < 16; ++i) { p0[i] = 0.f; p1[i] = 0.f; }
;             constexpr int PF = 3;
;             bf16x8 kf0[PF], kf1[PF];
; #pragma unroll
;             for (int i = 0; i < PF; ++i) { kf0[i] = *(const LAS bf16x8*)FA_KADDR(slot, 0, i); kf1[i] = *(const LAS bf16x8*)FA_KADDR(slot, 1, i); }
;             FA_SB();
; #pragma unroll
;             for (int ks = 0; ks < NKS; ++ks) {
;                 const bf16x8 a0 = kf0[ks % PF], a1 = kf1[ks % PF];
;                 p0 = FA_MFMA(a0, qr[ks], p0); p1 = FA_MFMA(a1, qr[ks], p1);
;                 if (ks + PF < NKS) { kf0[ks % PF] = *(const LAS bf16x8*)FA_KADDR(slot, 0, ks + PF); kf1[ks % PF] = *(const LAS bf16x8*)FA_KADDR(slot, 1, ks + PF); }
;                 FA_SB();
;             }
;             s16x4 vlo[2][4], vhh[2][4];
;             vtr8_issue<0>(vba, vlo[0], vhh[0]);
;             const bool full = (64 * t + 63 <= qw) && (64 * t >= qw + 31 - d.W) && (d.slope2 == 0.f);
;             if (!full) {
;                 const int dist0 = myq - 64 * t - 4 * hi;
; #pragma unroll
;                 for (int i = 0; i < 16; ++i) { const int d0 = dist0 - ((i & 3) + 8 * (i >> 2)), d1 = d0 - 32;
;                     p0[i] = ((unsigned)d0 <= (unsigned)d.W) ? __builtin_fmaf(-d.slope2, (float)d0, p0[i]) : NEG;
;                     p1[i] = ((unsigned)d1 <= (unsigned)d.W) ? __builtin_fmaf(-d.slope2, (float)d1, p1[i]) : NEG; }
.LBB0_517:
	s_cmp_le_i32 s62, s65
	s_cselect_b64 s[14:15], -1, 0
	s_add_i32 s4, s62, 63
	s_cmp_ge_i32 s4, s66
	s_cselect_b64 s[24:25], -1, 0
	s_and_b64 s[14:15], s[14:15], s[24:25]
	s_andn2_b64 vcc, exec, s[14:15]
	s_cbranch_vccnz .LBB0_523
	s_lshl_b32 s5, s64, 14
	s_add_i32 s14, s5, 0
	v_add3_u32 v72, s14, v161, v160
	v_add3_u32 v76, s14, v167, v160
	ds_read_b128 v[68:71], v72
	ds_read_b128 v[72:75], v72 offset:8192
	ds_read_b128 v[132:135], v76
	ds_read_b128 v[136:139], v76 offset:8192
	v_add3_u32 v76, s14, v168, v160
	ds_read_b128 v[140:143], v76
	ds_read_b128 v[144:147], v76 offset:8192
	v_add_u32_e32 v76, s5, v175
	v_add_u32_e32 v177, 0xc000, v76
	s_waitcnt lgkmcnt(0)
	v_mfma_f32_32x32x16_bf16 v[84:99], v[68:71], v[100:103], 0
	v_add3_u32 v153, s14, v169, v160
	ds_read_b128 v[178:181], v153
	ds_read_b128 v[182:185], v153 offset:8192
	v_mfma_f32_32x32x16_bf16 v[68:83], v[72:75], v[100:103], 0
	v_mfma_f32_32x32x16_bf16 v[84:99], v[132:135], v[104:107], v[84:99]
	v_mfma_f32_32x32x16_bf16 v[68:83], v[136:139], v[104:107], v[68:83]
	v_add3_u32 v136, s14, v170, v160
	ds_read_b128 v[132:135], v136
	ds_read_b128 v[136:139], v136 offset:8192
	v_mfma_f32_32x32x16_bf16 v[84:99], v[140:143], v[108:111], v[84:99]
	v_mfma_f32_32x32x16_bf16 v[68:83], v[144:147], v[108:111], v[68:83]
	v_add3_u32 v144, s14, v171, v160
	ds_read_b128 v[140:143], v144
	ds_read_b128 v[144:147], v144 offset:8192
	s_waitcnt lgkmcnt(0)
	v_mfma_f32_32x32x16_bf16 v[84:99], v[178:181], v[112:115], v[84:99]
	v_add3_u32 v153, s14, v172, v160
	v_mfma_f32_32x32x16_bf16 v[68:83], v[182:185], v[112:115], v[68:83]
	ds_read_b128 v[178:181], v153
	ds_read_b128 v[182:185], v153 offset:8192
	v_mfma_f32_32x32x16_bf16 v[84:99], v[132:135], v[116:119], v[84:99]
	v_mfma_f32_32x32x16_bf16 v[68:83], v[136:139], v[116:119], v[68:83]
	v_add3_u32 v136, s14, v173, v160
	ds_read_b128 v[132:135], v136
	ds_read_b128 v[136:139], v136 offset:8192
	v_mfma_f32_32x32x16_bf16 v[84:99], v[140:143], v[120:123], v[84:99]
	v_mfma_f32_32x32x16_bf16 v[68:83], v[144:147], v[120:123], v[68:83]
	s_waitcnt lgkmcnt(0)
	v_mfma_f32_32x32x16_bf16 v[84:99], v[178:181], v[124:127], v[84:99]
	v_mfma_f32_32x32x16_bf16 v[68:83], v[182:185], v[124:127], v[68:83]
	v_mfma_f32_32x32x16_bf16 v[84:99], v[132:135], v[128:131], v[84:99]
	v_mfma_f32_32x32x16_bf16 v[68:83], v[136:139], v[128:131], v[68:83]
	s_cmp_le_i32 s4, s22
	s_cselect_b64 s[4:5], -1, 0
	s_cmp_ge_i32 s62, s67
	s_cselect_b64 s[14:15], -1, 0
	ds_read_b64_tr_b16 v[144:145], v177 offset:0
	ds_read_b64_tr_b16 v[146:147], v177 offset:2048
	ds_read_b64_tr_b16 v[140:141], v177 offset:512
	ds_read_b64_tr_b16 v[142:143], v177 offset:2560
	ds_read_b64_tr_b16 v[136:137], v177 offset:1024
	ds_read_b64_tr_b16 v[138:139], v177 offset:3072
	ds_read_b64_tr_b16 v[132:133], v177 offset:1536
	ds_read_b64_tr_b16 v[134:135], v177 offset:3584
	s_and_b64 s[4:5], s[4:5], s[14:15]
	s_and_b64 s[4:5], s[4:5], s[40:41]
	s_and_b64 vcc, exec, s[4:5]
	s_cbranch_vccnz .LBB0_520
	v_add_u32_e32 v153, s62, v174
	v_or_b32_e32 v178, 3, v153
	v_or_b32_e32 v179, 2, v153
	v_sub_u32_e32 v196, v155, v178
	v_or_b32_e32 v178, 9, v153
	v_sub_u32_e32 v197, v0, v179
	v_or_b32_e32 v179, 8, v153
	v_sub_u32_e32 v200, v155, v178
	v_or_b32_e32 v178, 11, v153
	v_sub_u32_e32 v201, v0, v179
	v_or_b32_e32 v179, 10, v153
	v_sub_u32_e32 v214, v155, v178
	v_or_b32_e32 v178, 17, v153
	v_sub_u32_e32 v215, v0, v179
	v_or_b32_e32 v179, 16, v153
	v_sub_u32_e32 v226, v155, v178
	v_or_b32_e32 v178, 19, v153
	v_sub_u32_e32 v227, v0, v179
	v_or_b32_e32 v179, 18, v153
	v_sub_u32_e32 v230, v155, v178
	v_or_b32_e32 v178, 25, v153
	v_sub_u32_e32 v231, v0, v179
	v_or_b32_e32 v179, 24, v153
	v_sub_u32_e32 v234, v155, v178
	v_or_b32_e32 v178, 27, v153
	v_or_b32_e32 v153, 26, v153
	v_sub_u32_e32 v238, v155, v178
	v_sub_u32_e32 v239, v0, v153
	v_sub_u32_e32 v235, v0, v179
	v_cvt_f32_i32_e32 v179, v238
	v_cvt_f32_i32_e32 v178, v239
	v_cvt_f32_i32_e32 v181, v234
	v_cvt_f32_i32_e32 v180, v235
	v_mov_b32_e32 v153, v152
	v_cvt_f32_i32_e32 v183, v230
	v_cvt_f32_i32_e32 v182, v231
	v_fma_f32 v98, v152, v178, v98
	v_fma_f32 v99, v153, v179, v99
	v_cmp_gt_u32_e32 vcc, s55, v238
	v_cvt_f32_i32_e32 v185, v226
	v_cvt_f32_i32_e32 v184, v227
	v_cndmask_b32_e32 v99, v219, v99, vcc
	v_cmp_gt_u32_e32 vcc, s55, v239
	v_fma_f32 v96, v152, v180, v96
	v_fma_f32 v97, v153, v181, v97
	v_cvt_f32_i32_e32 v187, v214
	v_cndmask_b32_e32 v98, v219, v98, vcc
	v_cmp_gt_u32_e32 vcc, s55, v234
	v_cvt_f32_i32_e32 v186, v215
	v_fma_f32 v94, v152, v182, v94
	v_fma_f32 v95, v153, v183, v95
	v_cndmask_b32_e32 v97, v219, v97, vcc
	v_cmp_gt_u32_e32 vcc, s55, v235
	v_cvt_f32_i32_e32 v189, v200
	v_cvt_f32_i32_e32 v188, v201
	v_cndmask_b32_e32 v96, v219, v96, vcc
	v_cmp_gt_u32_e32 vcc, s55, v230
	v_fma_f32 v92, v152, v184, v92
	v_fma_f32 v93, v153, v185, v93
	v_cvt_f32_i32_e32 v191, v196
	v_cndmask_b32_e32 v95, v219, v95, vcc
	v_cmp_gt_u32_e32 vcc, s55, v231
	v_cvt_f32_i32_e32 v190, v197
	v_fma_f32 v90, v152, v186, v90
	v_fma_f32 v91, v153, v187, v91
	v_cndmask_b32_e32 v94, v219, v94, vcc
	v_cmp_gt_u32_e32 vcc, s55, v226
	v_add_u32_e32 v154, -1, v176
	v_cvt_f32_i32_e32 v193, v154
	v_cndmask_b32_e32 v93, v219, v93, vcc
	v_cmp_gt_u32_e32 vcc, s55, v227
	v_cvt_f32_i32_e32 v192, v176
	v_fma_f32 v88, v152, v188, v88
	v_fma_f32 v89, v153, v189, v89
	v_cndmask_b32_e32 v92, v219, v92, vcc
	v_cmp_gt_u32_e32 vcc, s55, v214
	v_subrev_u32_e32 v240, 32, v239
	v_subrev_u32_e32 v241, 32, v238
	v_cndmask_b32_e32 v91, v219, v91, vcc
	v_cmp_gt_u32_e32 vcc, s55, v215
	v_fma_f32 v86, v152, v190, v86
	v_fma_f32 v87, v153, v191, v87
	v_cvt_f32_i32_e32 v179, v241
	v_cndmask_b32_e32 v90, v219, v90, vcc
; template <int DQK, bool HAS_LSE>
; __device__ __forceinline__ void unit(LAS unsigned char* lds, const Desc& d) {
;     ...
;                 for (int i = 0; i < 16; ++i) { const int d0 = dist0 - ((i & 3) + 8 * (i >> 2)), d1 = d0 - 32;
;                     p0[i] = ((unsigned)d0 <= (unsigned)d.W) ? __builtin_fmaf(-d.slope2, (float)d0, p0[i]) : NEG;
;                     p1[i] = ((unsigned)d1 <= (unsigned)d.W) ? __builtin_fmaf(-d.slope2, (float)d1, p1[i]) : NEG; }
;             }
;             float mx = fmaxf(p0[0], p1[0]);
; #pragma unroll
;             for (int i = 1; i < 16; ++i) mx = fmaxf(mx, fmaxf(p0[i], p1[i]));
;             mx = fmaxf(mx, __shfl_xor(mx, 32));
;             const float mn = fmaxf(m, mx), corr = __builtin_amdgcn_exp2f(m - mn); const bool grew = __any(mn > m); m = mn;
;             float ls = 0.f;
; #pragma unroll
;             for (int i = 0; i < 16; ++i) { p0[i] = __builtin_amdgcn_exp2f(p0[i] - mn); p1[i] = __builtin_amdgcn_exp2f(p1[i] - mn); ls += p0[i] + p1[i]; }
;             l = l * corr + ls;
;             if (grew) {
; #pragma unroll
;                 for (int db = 0; db < 4; ++db)
; #pragma unroll
;                     for (int i = 0; i < 16; ++i) o[db][i] *= corr;
;             }
	v_cmp_gt_u32_e32 vcc, s55, v200
	v_cvt_f32_i32_e32 v178, v240
	v_subrev_u32_e32 v236, 32, v235
	v_cndmask_b32_e32 v89, v219, v89, vcc
	v_cmp_gt_u32_e32 vcc, s55, v201
	v_subrev_u32_e32 v237, 32, v234
	v_fma_f32 v84, v156, v192, v84
	v_fma_f32 v85, v157, v193, v85
	v_cndmask_b32_e32 v88, v219, v88, vcc
	v_cmp_gt_u32_e32 vcc, s55, v196
	v_cvt_f32_i32_e32 v181, v237
	v_cvt_f32_i32_e32 v180, v236
	v_cndmask_b32_e32 v87, v219, v87, vcc
	v_cmp_gt_u32_e32 vcc, s55, v197
	v_subrev_u32_e32 v232, 32, v231
	v_subrev_u32_e32 v233, 32, v230
	v_cndmask_b32_e32 v86, v219, v86, vcc
	v_cmp_gt_u32_e32 vcc, s55, v154
	v_cvt_f32_i32_e32 v183, v233
	v_cvt_f32_i32_e32 v182, v232
	v_cndmask_b32_e32 v85, v219, v85, vcc
	v_cmp_gt_u32_e32 vcc, s55, v176
	v_fma_f32 v82, v152, v178, v82
	v_fma_f32 v83, v153, v179, v83
	v_subrev_u32_e32 v228, 32, v227
	v_cndmask_b32_e32 v84, v219, v84, vcc
	v_cmp_gt_u32_e32 vcc, s55, v241
	v_subrev_u32_e32 v229, 32, v226
	v_cvt_f32_i32_e32 v185, v229
	v_cndmask_b32_e32 v83, v219, v83, vcc
	v_cmp_gt_u32_e32 vcc, s55, v240
	v_cvt_f32_i32_e32 v184, v228
	v_fma_f32 v80, v152, v180, v80
	v_fma_f32 v81, v153, v181, v81
	v_cndmask_b32_e32 v82, v219, v82, vcc
	v_cmp_gt_u32_e32 vcc, s55, v237
	v_subrev_u32_e32 v224, 32, v215
	v_subrev_u32_e32 v225, 32, v214
	v_cndmask_b32_e32 v81, v219, v81, vcc
	v_cmp_gt_u32_e32 vcc, s55, v236
	v_cvt_f32_i32_e32 v187, v225
	v_cvt_f32_i32_e32 v186, v224
	v_fma_f32 v78, v152, v182, v78
	v_fma_f32 v79, v153, v183, v79
	v_cndmask_b32_e32 v80, v219, v80, vcc
	v_cmp_gt_u32_e32 vcc, s55, v233
	v_subrev_u32_e32 v202, 32, v201
	v_subrev_u32_e32 v203, 32, v200
	v_cndmask_b32_e32 v79, v219, v79, vcc
	v_cmp_gt_u32_e32 vcc, s55, v232
	v_cvt_f32_i32_e32 v189, v203
	v_cvt_f32_i32_e32 v188, v202
	v_fma_f32 v76, v152, v184, v76
	v_fma_f32 v77, v153, v185, v77
	v_cndmask_b32_e32 v78, v219, v78, vcc
	v_cmp_gt_u32_e32 vcc, s55, v229
	v_subrev_u32_e32 v198, 32, v197
	v_subrev_u32_e32 v199, 32, v196
	v_cndmask_b32_e32 v77, v219, v77, vcc
	v_cmp_gt_u32_e32 vcc, s55, v228
	v_cvt_f32_i32_e32 v191, v199
	v_cvt_f32_i32_e32 v190, v198
	v_fma_f32 v74, v152, v186, v74
	v_fma_f32 v75, v153, v187, v75
	v_cndmask_b32_e32 v76, v219, v76, vcc
	v_cmp_gt_u32_e32 vcc, s55, v225
	v_subrev_u32_e32 v194, 32, v176
	v_subrev_u32_e32 v195, 33, v176
	v_cndmask_b32_e32 v75, v219, v75, vcc
	v_cmp_gt_u32_e32 vcc, s55, v224
	v_cvt_f32_i32_e32 v193, v195
	v_cvt_f32_i32_e32 v192, v194
	v_fma_f32 v72, v152, v188, v72
	v_fma_f32 v73, v153, v189, v73
	v_cndmask_b32_e32 v74, v219, v74, vcc
	v_cmp_gt_u32_e32 vcc, s55, v203
	v_fma_f32 v70, v152, v190, v70
	v_fma_f32 v71, v153, v191, v71
	v_fma_f32 v68, v156, v192, v68
	v_fma_f32 v69, v157, v193, v69
	v_cndmask_b32_e32 v73, v219, v73, vcc
	v_cmp_gt_u32_e32 vcc, s55, v202
	s_nop 1
	v_cndmask_b32_e32 v72, v219, v72, vcc
	v_cmp_gt_u32_e32 vcc, s55, v199
	s_nop 1
	v_cndmask_b32_e32 v71, v219, v71, vcc
	v_cmp_gt_u32_e32 vcc, s55, v198
	s_nop 1
	v_cndmask_b32_e32 v70, v219, v70, vcc
	v_cmp_gt_u32_e32 vcc, s55, v195
	s_nop 1
	v_cndmask_b32_e32 v69, v219, v69, vcc
	v_cmp_gt_u32_e32 vcc, s55, v194
	s_nop 1
	v_cndmask_b32_e32 v68, v219, v68, vcc
.LBB0_520:
	s_nop 3
	v_max_f32_e32 v153, v69, v69
	v_max_f32_e32 v154, v85, v85
	v_max_f32_e32 v153, v154, v153
	v_max_f32_e32 v154, v70, v70
	v_max_f32_e32 v178, v86, v86
	v_max_f32_e32 v154, v178, v154
	v_max_f32_e32 v178, v71, v71
	v_max_f32_e32 v179, v87, v87
	v_max3_f32 v153, v84, v68, v153
	v_max_f32_e32 v178, v179, v178
	v_max3_f32 v153, v153, v154, v178
	v_max_f32_e32 v154, v72, v72
	v_max_f32_e32 v178, v88, v88
	v_max_f32_e32 v154, v178, v154
	v_max_f32_e32 v178, v73, v73
	v_max_f32_e32 v179, v89, v89
	v_max_f32_e32 v178, v179, v178
	v_max3_f32 v153, v153, v154, v178
	v_max_f32_e32 v154, v74, v74
	v_max_f32_e32 v178, v90, v90
	v_max_f32_e32 v154, v178, v154
	v_max_f32_e32 v178, v75, v75
	v_max_f32_e32 v179, v91, v91
	v_max_f32_e32 v178, v179, v178
	v_max3_f32 v153, v153, v154, v178
	v_max_f32_e32 v154, v76, v76
	v_max_f32_e32 v178, v92, v92
	v_max_f32_e32 v154, v178, v154
	v_max_f32_e32 v178, v77, v77
	v_max_f32_e32 v179, v93, v93
	v_max_f32_e32 v178, v179, v178
	v_max3_f32 v153, v153, v154, v178
	v_max_f32_e32 v154, v78, v78
	v_max_f32_e32 v178, v94, v94
	v_max_f32_e32 v154, v178, v154
	v_max_f32_e32 v178, v79, v79
	v_max_f32_e32 v179, v95, v95
	v_max_f32_e32 v178, v179, v178
	v_max3_f32 v153, v153, v154, v178
	v_max_f32_e32 v154, v80, v80
	v_max_f32_e32 v178, v96, v96
	v_max_f32_e32 v154, v178, v154
	v_max_f32_e32 v178, v81, v81
	v_max_f32_e32 v179, v97, v97
	v_max_f32_e32 v178, v179, v178
	v_max3_f32 v153, v153, v154, v178
	v_max_f32_e32 v154, v82, v82
	v_max_f32_e32 v178, v98, v98
	v_max_f32_e32 v154, v178, v154
	v_max_f32_e32 v178, v83, v83
	v_max_f32_e32 v179, v99, v99
	v_max_f32_e32 v178, v179, v178
	v_cmp_lt_i32_e32 vcc, v218, v212
	v_max3_f32 v153, v153, v154, v178
	s_nop 0
	v_cndmask_b32_e32 v154, v211, v218, vcc
	v_lshlrev_b32_e32 v154, 2, v154
	ds_bpermute_b32 v154, v154, v153
	s_waitcnt lgkmcnt(0)
	v_max3_f32 v153, v67, v153, v154
	v_sub_f32_e32 v154, v67, v153
	v_exp_f32_e32 v154, v154
	v_cmp_gt_f32_e32 vcc, v153, v67
	s_cbranch_vccz .LBB0_522
	v_mul_f32_e32 v64, v64, v154
	v_mul_f32_e32 v65, v65, v154
	v_mul_f32_e32 v62, v62, v154
	v_mul_f32_e32 v63, v63, v154
	v_mul_f32_e32 v60, v60, v154
	v_mul_f32_e32 v61, v61, v154
	v_mul_f32_e32 v58, v58, v154
	v_mul_f32_e32 v59, v59, v154
	v_mul_f32_e32 v56, v56, v154
	v_mul_f32_e32 v57, v57, v154
	v_mul_f32_e32 v54, v54, v154
	v_mul_f32_e32 v55, v55, v154
	v_mul_f32_e32 v52, v52, v154
	v_mul_f32_e32 v53, v53, v154
	v_mul_f32_e32 v50, v50, v154
	v_mul_f32_e32 v51, v51, v154
	v_mul_f32_e32 v48, v48, v154
	v_mul_f32_e32 v49, v49, v154
	v_mul_f32_e32 v46, v46, v154
	v_mul_f32_e32 v47, v47, v154
	v_mul_f32_e32 v44, v44, v154
	v_mul_f32_e32 v45, v45, v154
	v_mul_f32_e32 v42, v42, v154
	v_mul_f32_e32 v43, v43, v154
	v_mul_f32_e32 v40, v40, v154
	v_mul_f32_e32 v41, v41, v154
	v_mul_f32_e32 v38, v38, v154
	v_mul_f32_e32 v39, v39, v154
	v_mul_f32_e32 v36, v36, v154
	v_mul_f32_e32 v37, v37, v154
	v_mul_f32_e32 v34, v34, v154
	v_mul_f32_e32 v35, v35, v154
	v_mul_f32_e32 v32, v32, v154
	v_mul_f32_e32 v33, v33, v154
	v_mul_f32_e32 v30, v30, v154
	v_mul_f32_e32 v31, v31, v154
	v_mul_f32_e32 v28, v28, v154
	v_mul_f32_e32 v29, v29, v154
	v_mul_f32_e32 v26, v26, v154
	v_mul_f32_e32 v27, v27, v154
	v_mul_f32_e32 v24, v24, v154
	v_mul_f32_e32 v25, v25, v154
	v_mul_f32_e32 v22, v22, v154
	v_mul_f32_e32 v23, v23, v154
	v_mul_f32_e32 v20, v20, v154
	v_mul_f32_e32 v21, v21, v154
	v_mul_f32_e32 v18, v18, v154
	v_mul_f32_e32 v19, v19, v154
	v_mul_f32_e32 v16, v16, v154
	v_mul_f32_e32 v17, v17, v154
	v_mul_f32_e32 v14, v14, v154
	v_mul_f32_e32 v15, v15, v154
	v_mul_f32_e32 v12, v12, v154
	v_mul_f32_e32 v13, v13, v154
	v_mul_f32_e32 v10, v10, v154
	v_mul_f32_e32 v11, v11, v154
	v_mul_f32_e32 v8, v8, v154
	v_mul_f32_e32 v9, v9, v154
	v_mul_f32_e32 v6, v6, v154
	v_mul_f32_e32 v7, v7, v154
	v_mul_f32_e32 v4, v4, v154
	v_mul_f32_e32 v5, v5, v154
	v_mul_f32_e32 v2, v2, v154
	v_mul_f32_e32 v3, v3, v154

; #define LAS __attribute__((address_space(3)))
; #define FA_MFMA(a, b, c) __builtin_amdgcn_mfma_f32_32x32x16_bf16((a), (b), (c), 0, 0, 0)
; #define FA_SB() __builtin_amdgcn_sched_barrier(0)
; template <int DQK, bool HAS_LSE>
; __device__ __forceinline__ void unit(LAS unsigned char* lds, const Desc& d) {
;     ...
;         const bool active = (64 * t <= qw + 31) && (64 * t + 63 >= qw - d.W);
;         if (active) {
;             const unsigned vba = (unsigned)(unsigned long)(lds + vfo + slot * VT);
;             f32x16 p0, p1;
; #pragma unroll
;             for (int i = 0; i < 16; ++i) { p0[i] = 0.f; p1[i] = 0.f; }
;             constexpr int PF = 3;
;             bf16x8 kf0[PF], kf1[PF];
; #pragma unroll
;             for (int i = 0; i < PF; ++i) { kf0[i] = *(const LAS bf16x8*)FA_KADDR(slot, 0, i); kf1[i] = *(const LAS bf16x8*)FA_KADDR(slot, 1, i); }
;             FA_SB();
; #pragma unroll
;             for (int ks = 0; ks < NKS; ++ks) {
;                 const bf16x8 a0 = kf0[ks % PF], a1 = kf1[ks % PF];
;                 p0 = FA_MFMA(a0, qr[ks], p0); p1 = FA_MFMA(a1, qr[ks], p1);
;                 if (ks + PF < NKS) { kf0[ks % PF] = *(const LAS bf16x8*)FA_KADDR(slot, 0, ks + PF); kf1[ks % PF] = *(const LAS bf16x8*)FA_KADDR(slot, 1, ks + PF); }
;                 FA_SB();
;             }
;             s16x4 vlo[2][4], vhh[2][4];
;             vtr8_issue<0>(vba, vlo[0], vhh[0]);
;             const bool full = (64 * t + 63 <= qw) && (64 * t >= qw + 31 - d.W) && (d.slope2 == 0.f);
;             if (!full) {
;                 const int dist0 = myq - 64 * t - 4 * hi;
; #pragma unroll
;                 for (int i = 0; i < 16; ++i) { const int d0 = dist0 - ((i & 3) + 8 * (i >> 2)), d1 = d0 - 32;
;                     p0[i] = ((unsigned)d0 <= (unsigned)d.W) ? __builtin_fmaf(-d.slope2, (float)d0, p0[i]) : NEG;
;                     p1[i] = ((unsigned)d1 <= (unsigned)d.W) ? __builtin_fmaf(-d.slope2, (float)d1, p1[i]) : NEG; }
.LBB0_1994:
	s_cmp_le_i32 s44, s66
	s_cselect_b64 s[14:15], -1, 0
	s_add_i32 s4, s44, 63
	s_cmp_ge_i32 s4, s67
	s_cselect_b64 s[24:25], -1, 0
	s_and_b64 s[14:15], s[14:15], s[24:25]
	s_andn2_b64 vcc, exec, s[14:15]
	s_cbranch_vccnz .LBB0_2000
	s_mul_i32 s5, s45, 0x6000
	s_add_i32 s5, s5, 0
	v_add3_u32 v0, s5, v178, v175
	v_add3_u32 v186, s5, v179, v175
	v_add3_u32 v189, s5, v180, v175
	ds_read_b128 v[66:69], v0
	ds_read_b128 v[70:73], v0 offset:12288
	ds_read_b128 v[146:149], v186
	ds_read_b128 v[150:153], v186 offset:12288
	ds_read_b128 v[154:157], v189
	ds_read_b128 v[158:161], v189 offset:12288
	v_lshl_add_u32 v185, s45, 14, v183
	s_waitcnt lgkmcnt(0)
	v_mfma_f32_32x32x16_bf16 v[82:97], v[66:69], v[98:101], 0
	v_add3_u32 v198, s5, v181, v175
	ds_read_b128 v[190:193], v198
	ds_read_b128 v[194:197], v198 offset:12288
	v_mfma_f32_32x32x16_bf16 v[66:81], v[70:73], v[98:101], 0
	v_mfma_f32_32x32x16_bf16 v[82:97], v[146:149], v[102:105], v[82:97]
	v_mfma_f32_32x32x16_bf16 v[66:81], v[150:153], v[102:105], v[66:81]
	ds_read_b128 v[146:149], v0 offset:128
	ds_read_b128 v[150:153], v0 offset:12416
	v_mfma_f32_32x32x16_bf16 v[82:97], v[154:157], v[106:109], v[82:97]
	v_mfma_f32_32x32x16_bf16 v[66:81], v[158:161], v[106:109], v[66:81]
	ds_read_b128 v[154:157], v186 offset:128
	ds_read_b128 v[158:161], v186 offset:12416
	s_waitcnt lgkmcnt(0)
	v_mfma_f32_32x32x16_bf16 v[82:97], v[190:193], v[110:113], v[82:97]
	v_mfma_f32_32x32x16_bf16 v[66:81], v[194:197], v[110:113], v[66:81]
	ds_read_b128 v[190:193], v189 offset:128
	ds_read_b128 v[194:197], v189 offset:12416
	v_mfma_f32_32x32x16_bf16 v[82:97], v[146:149], v[114:117], v[82:97]
	v_mfma_f32_32x32x16_bf16 v[66:81], v[150:153], v[114:117], v[66:81]
	ds_read_b128 v[146:149], v198 offset:128
	ds_read_b128 v[150:153], v198 offset:12416
	v_mfma_f32_32x32x16_bf16 v[82:97], v[154:157], v[118:121], v[82:97]
	v_mfma_f32_32x32x16_bf16 v[66:81], v[158:161], v[118:121], v[66:81]
	ds_read_b128 v[154:157], v0 offset:256
	ds_read_b128 v[158:161], v0 offset:12544
	s_waitcnt lgkmcnt(0)
	v_mfma_f32_32x32x16_bf16 v[82:97], v[190:193], v[122:125], v[82:97]
	v_mfma_f32_32x32x16_bf16 v[66:81], v[194:197], v[122:125], v[66:81]
	ds_read_b128 v[190:193], v186 offset:256
	ds_read_b128 v[194:197], v186 offset:12544
	v_mfma_f32_32x32x16_bf16 v[82:97], v[146:149], v[126:129], v[82:97]
	v_mfma_f32_32x32x16_bf16 v[66:81], v[150:153], v[126:129], v[66:81]
	ds_read_b128 v[146:149], v189 offset:256
	ds_read_b128 v[150:153], v189 offset:12544
	v_mfma_f32_32x32x16_bf16 v[82:97], v[154:157], v[130:133], v[82:97]
	v_mfma_f32_32x32x16_bf16 v[66:81], v[158:161], v[130:133], v[66:81]
	ds_read_b128 v[154:157], v198 offset:256
	ds_read_b128 v[158:161], v198 offset:12544
	s_waitcnt lgkmcnt(0)
	v_mfma_f32_32x32x16_bf16 v[82:97], v[190:193], v[134:137], v[82:97]
	v_mfma_f32_32x32x16_bf16 v[66:81], v[194:197], v[134:137], v[66:81]
	v_mfma_f32_32x32x16_bf16 v[82:97], v[146:149], v[138:141], v[82:97]
	v_mfma_f32_32x32x16_bf16 v[66:81], v[150:153], v[138:141], v[66:81]
	v_mfma_f32_32x32x16_bf16 v[82:97], v[154:157], v[142:145], v[82:97]
	v_mfma_f32_32x32x16_bf16 v[66:81], v[158:161], v[142:145], v[66:81]
	s_cmp_le_i32 s4, s52
	s_cselect_b64 s[4:5], -1, 0
	s_cmp_ge_i32 s44, s74
	ds_read_b64_tr_b16 v[158:159], v185 offset:0
	ds_read_b64_tr_b16 v[160:161], v185 offset:2048
	ds_read_b64_tr_b16 v[154:155], v185 offset:512
	ds_read_b64_tr_b16 v[156:157], v185 offset:2560
	ds_read_b64_tr_b16 v[150:151], v185 offset:1024
	ds_read_b64_tr_b16 v[152:153], v185 offset:3072
	ds_read_b64_tr_b16 v[146:147], v185 offset:1536
	ds_read_b64_tr_b16 v[148:149], v185 offset:3584
	s_cselect_b64 s[14:15], -1, 0
	s_and_b64 s[4:5], s[4:5], s[14:15]
	s_and_b64 vcc, exec, s[4:5]
	s_cbranch_vccnz .LBB0_1997
	v_add_u32_e32 v0, s44, v182
	v_or_b32_e32 v190, 3, v0
	v_or_b32_e32 v191, 2, v0
	v_sub_u32_e32 v215, v167, v190
	v_or_b32_e32 v190, 9, v0
	v_sub_u32_e32 v226, v174, v191
	v_or_b32_e32 v191, 8, v0
	v_sub_u32_e32 v229, v167, v190
	v_or_b32_e32 v190, 11, v0
	v_sub_u32_e32 v230, v174, v191
	v_or_b32_e32 v191, 10, v0
	v_sub_u32_e32 v233, v167, v190
	v_or_b32_e32 v190, 17, v0
	v_sub_u32_e32 v234, v174, v191
	v_or_b32_e32 v191, 16, v0
	v_sub_u32_e32 v237, v167, v190
	v_or_b32_e32 v190, 19, v0
	v_sub_u32_e32 v238, v174, v191
	v_or_b32_e32 v191, 18, v0
	v_sub_u32_e32 v241, v167, v190
	v_or_b32_e32 v190, 25, v0
	v_sub_u32_e32 v242, v174, v191
	v_or_b32_e32 v191, 24, v0
	v_sub_u32_e32 v245, v167, v190
	v_or_b32_e32 v190, 27, v0
	v_or_b32_e32 v0, 26, v0
	v_sub_u32_e32 v249, v167, v190
	v_sub_u32_e32 v0, v174, v0
	v_sub_u32_e32 v246, v174, v191
	v_cvt_f32_i32_e32 v191, v249
	v_cvt_f32_i32_e32 v190, v0
	v_cvt_f32_i32_e32 v193, v245
	v_cvt_f32_i32_e32 v192, v246
	v_cvt_f32_i32_e32 v195, v241
	v_cvt_f32_i32_e32 v194, v242
	v_fma_f32 v96, v190, s84, v96
	v_fma_f32 v97, v191, s84, v97
	v_cmp_gt_u32_e32 vcc, s17, v249
	v_cvt_f32_i32_e32 v197, v237
	v_cvt_f32_i32_e32 v196, v238
	v_cndmask_b32_e32 v97, v219, v97, vcc
	v_cmp_gt_u32_e32 vcc, s17, v0
	v_fma_f32 v94, v192, s84, v94
	v_fma_f32 v95, v193, s84, v95
	v_cvt_f32_i32_e32 v199, v233
	v_cndmask_b32_e32 v96, v219, v96, vcc
	v_cmp_gt_u32_e32 vcc, s17, v245
	v_cvt_f32_i32_e32 v198, v234
	v_fma_f32 v92, v194, s84, v92
	v_fma_f32 v93, v195, s84, v93
	v_cndmask_b32_e32 v95, v219, v95, vcc
	v_cmp_gt_u32_e32 vcc, s17, v246
	v_cvt_f32_i32_e32 v201, v229
	v_cvt_f32_i32_e32 v200, v230
	v_cndmask_b32_e32 v94, v219, v94, vcc
	v_cmp_gt_u32_e32 vcc, s17, v241
	v_fma_f32 v90, v196, s84, v90
	v_fma_f32 v91, v197, s84, v91
	v_cvt_f32_i32_e32 v203, v215
	v_cndmask_b32_e32 v93, v219, v93, vcc
	v_cmp_gt_u32_e32 vcc, s17, v242
	v_cvt_f32_i32_e32 v202, v226
; template <int DQK, bool HAS_LSE>
; __device__ __forceinline__ void unit(LAS unsigned char* lds, const Desc& d) {
;     ...
;                 for (int i = 0; i < 16; ++i) { const int d0 = dist0 - ((i & 3) + 8 * (i >> 2)), d1 = d0 - 32;
;                     p0[i] = ((unsigned)d0 <= (unsigned)d.W) ? __builtin_fmaf(-d.slope2, (float)d0, p0[i]) : NEG;
;                     p1[i] = ((unsigned)d1 <= (unsigned)d.W) ? __builtin_fmaf(-d.slope2, (float)d1, p1[i]) : NEG; }
	v_fma_f32 v88, v198, s84, v88
	v_fma_f32 v89, v199, s84, v89
	v_cndmask_b32_e32 v92, v219, v92, vcc
	v_cmp_gt_u32_e32 vcc, s17, v237
	v_add_u32_e32 v186, -1, v184
	v_cvt_f32_i32_e32 v225, v186
	v_cndmask_b32_e32 v91, v219, v91, vcc
	v_cmp_gt_u32_e32 vcc, s17, v238
	v_cvt_f32_i32_e32 v224, v184
	v_fma_f32 v86, v200, s84, v86
	v_fma_f32 v87, v201, s84, v87
	v_cndmask_b32_e32 v90, v219, v90, vcc
	v_cmp_gt_u32_e32 vcc, s17, v233
	v_subrev_u32_e32 v250, 32, v0
	v_subrev_u32_e32 v251, 32, v249
	v_cndmask_b32_e32 v89, v219, v89, vcc
	v_cmp_gt_u32_e32 vcc, s17, v234
	v_fma_f32 v84, v202, s84, v84
	v_fma_f32 v85, v203, s84, v85
	v_cvt_f32_i32_e32 v191, v251
	v_cndmask_b32_e32 v88, v219, v88, vcc
	v_cmp_gt_u32_e32 vcc, s17, v229
	v_cvt_f32_i32_e32 v190, v250
	v_subrev_u32_e32 v247, 32, v246
	v_cndmask_b32_e32 v87, v219, v87, vcc
	v_cmp_gt_u32_e32 vcc, s17, v230
	v_subrev_u32_e32 v248, 32, v245
	v_fma_f32 v82, v224, s84, v82
	v_fma_f32 v83, v225, s84, v83
	v_cndmask_b32_e32 v86, v219, v86, vcc
	v_cmp_gt_u32_e32 vcc, s17, v215
	v_cvt_f32_i32_e32 v193, v248
	v_cvt_f32_i32_e32 v192, v247
	v_cndmask_b32_e32 v85, v219, v85, vcc
	v_cmp_gt_u32_e32 vcc, s17, v226
	v_subrev_u32_e32 v243, 32, v242
	v_subrev_u32_e32 v244, 32, v241
	v_cndmask_b32_e32 v84, v219, v84, vcc
	v_cmp_gt_u32_e32 vcc, s17, v186
	v_cvt_f32_i32_e32 v195, v244
	v_cvt_f32_i32_e32 v194, v243
	v_cndmask_b32_e32 v83, v219, v83, vcc
	v_cmp_gt_u32_e32 vcc, s17, v184
	v_fma_f32 v80, v190, s84, v80
	v_fma_f32 v81, v191, s84, v81
	v_subrev_u32_e32 v239, 32, v238
	v_cndmask_b32_e32 v82, v219, v82, vcc
	v_cmp_gt_u32_e32 vcc, s17, v251
	v_subrev_u32_e32 v240, 32, v237
	v_cvt_f32_i32_e32 v197, v240
	v_cndmask_b32_e32 v81, v219, v81, vcc
	v_cmp_gt_u32_e32 vcc, s17, v250
	v_cvt_f32_i32_e32 v196, v239
	v_fma_f32 v78, v192, s84, v78
	v_fma_f32 v79, v193, s84, v79
	v_cndmask_b32_e32 v80, v219, v80, vcc
	v_cmp_gt_u32_e32 vcc, s17, v248
	v_subrev_u32_e32 v235, 32, v234
	v_subrev_u32_e32 v236, 32, v233
	v_cndmask_b32_e32 v79, v219, v79, vcc
	v_cmp_gt_u32_e32 vcc, s17, v247
	v_cvt_f32_i32_e32 v199, v236
	v_cvt_f32_i32_e32 v198, v235
	v_fma_f32 v76, v194, s84, v76
	v_fma_f32 v77, v195, s84, v77
	v_cndmask_b32_e32 v78, v219, v78, vcc
	v_cmp_gt_u32_e32 vcc, s17, v244
	v_subrev_u32_e32 v231, 32, v230
	v_subrev_u32_e32 v232, 32, v229
	v_cndmask_b32_e32 v77, v219, v77, vcc
	v_cmp_gt_u32_e32 vcc, s17, v243
	v_cvt_f32_i32_e32 v201, v232
	v_cvt_f32_i32_e32 v200, v231
	v_fma_f32 v74, v196, s84, v74
	v_fma_f32 v75, v197, s84, v75
	v_cndmask_b32_e32 v76, v219, v76, vcc
	v_cmp_gt_u32_e32 vcc, s17, v240
	v_subrev_u32_e32 v227, 32, v226
	v_subrev_u32_e32 v228, 32, v215
	v_cndmask_b32_e32 v75, v219, v75, vcc
	v_cmp_gt_u32_e32 vcc, s17, v239
	v_cvt_f32_i32_e32 v203, v228
	v_cvt_f32_i32_e32 v202, v227
	v_fma_f32 v72, v198, s84, v72
	v_fma_f32 v73, v199, s84, v73
	v_cndmask_b32_e32 v74, v219, v74, vcc
	v_cmp_gt_u32_e32 vcc, s17, v236
	v_subrev_u32_e32 v189, 32, v184
	v_subrev_u32_e32 v214, 33, v184
	v_cndmask_b32_e32 v73, v219, v73, vcc
	v_cmp_gt_u32_e32 vcc, s17, v235
	v_cvt_f32_i32_e32 v225, v214
	v_cvt_f32_i32_e32 v224, v189
	v_fma_f32 v70, v200, s84, v70
	v_fma_f32 v71, v201, s84, v71
	v_cndmask_b32_e32 v72, v219, v72, vcc
	v_cmp_gt_u32_e32 vcc, s17, v232
	v_fma_f32 v68, v202, s84, v68
	v_fma_f32 v69, v203, s84, v69
	v_fma_f32 v66, v224, s84, v66
	v_fma_f32 v67, v225, s84, v67
	v_cndmask_b32_e32 v71, v219, v71, vcc
	v_cmp_gt_u32_e32 vcc, s17, v231
	s_nop 1
	v_cndmask_b32_e32 v70, v219, v70, vcc
	v_cmp_gt_u32_e32 vcc, s17, v228
	s_nop 1
	v_cndmask_b32_e32 v69, v219, v69, vcc
	v_cmp_gt_u32_e32 vcc, s17, v227
	s_nop 1
	v_cndmask_b32_e32 v68, v219, v68, vcc
	v_cmp_gt_u32_e32 vcc, s17, v214
	s_nop 1
	v_cndmask_b32_e32 v67, v219, v67, vcc
	v_cmp_gt_u32_e32 vcc, s17, v189
	s_nop 1
	v_cndmask_b32_e32 v66, v219, v66, vcc
; template <int DQK, bool HAS_LSE>
; __device__ __forceinline__ void unit(LAS unsigned char* lds, const Desc& d) {
;     ...
;             float mx = fmaxf(p0[0], p1[0]);
; #pragma unroll
;             for (int i = 1; i < 16; ++i) mx = fmaxf(mx, fmaxf(p0[i], p1[i]));
;             mx = fmaxf(mx, __shfl_xor(mx, 32));
;             const float mn = fmaxf(m, mx), corr = __builtin_amdgcn_exp2f(m - mn); const bool grew = __any(mn > m); m = mn;
;             float ls = 0.f;
; #pragma unroll
;             for (int i = 0; i < 16; ++i) { p0[i] = __builtin_amdgcn_exp2f(p0[i] - mn); p1[i] = __builtin_amdgcn_exp2f(p1[i] - mn); ls += p0[i] + p1[i]; }
;             l = l * corr + ls;
;             if (grew) {
; #pragma unroll
;                 for (int db = 0; db < 4; ++db)
; #pragma unroll
;                     for (int i = 0; i < 16; ++i) o[db][i] *= corr;
;             }
.LBB0_1997:
	s_nop 4
	v_max_f32_e32 v0, v67, v67
	v_max_f32_e32 v186, v83, v83
	v_max_f32_e32 v0, v186, v0
	v_max_f32_e32 v186, v68, v68
	v_max_f32_e32 v189, v84, v84
	v_max_f32_e32 v186, v189, v186
	v_max_f32_e32 v189, v69, v69
	v_max_f32_e32 v190, v85, v85
	v_max3_f32 v0, v82, v66, v0
	v_max_f32_e32 v189, v190, v189
	v_max3_f32 v0, v0, v186, v189
	v_max_f32_e32 v186, v70, v70
	v_max_f32_e32 v189, v86, v86
	v_max_f32_e32 v186, v189, v186
	v_max_f32_e32 v189, v71, v71
	v_max_f32_e32 v190, v87, v87
	v_max_f32_e32 v189, v190, v189
	v_max3_f32 v0, v0, v186, v189
	v_max_f32_e32 v186, v72, v72
	v_max_f32_e32 v189, v88, v88
	v_max_f32_e32 v186, v189, v186
	v_max_f32_e32 v189, v73, v73
	v_max_f32_e32 v190, v89, v89
	v_max_f32_e32 v189, v190, v189
	v_max3_f32 v0, v0, v186, v189
	v_max_f32_e32 v186, v74, v74
	v_max_f32_e32 v189, v90, v90
	v_max_f32_e32 v186, v189, v186
	v_max_f32_e32 v189, v75, v75
	v_max_f32_e32 v190, v91, v91
	v_max_f32_e32 v189, v190, v189
	v_max3_f32 v0, v0, v186, v189
	v_max_f32_e32 v186, v76, v76
	v_max_f32_e32 v189, v92, v92
	v_max_f32_e32 v186, v189, v186
	v_max_f32_e32 v189, v77, v77
	v_max_f32_e32 v190, v93, v93
	v_max_f32_e32 v189, v190, v189
	v_max3_f32 v0, v0, v186, v189
	v_max_f32_e32 v186, v78, v78
	v_max_f32_e32 v189, v94, v94
	v_max_f32_e32 v186, v189, v186
	v_max_f32_e32 v189, v79, v79
	v_max_f32_e32 v190, v95, v95
	v_max_f32_e32 v189, v190, v189
	v_max3_f32 v0, v0, v186, v189
	v_max_f32_e32 v186, v80, v80
	v_max_f32_e32 v189, v96, v96
	v_max_f32_e32 v186, v189, v186
	v_max_f32_e32 v189, v81, v81
	v_max_f32_e32 v190, v97, v97
	v_max_f32_e32 v189, v190, v189
	v_cmp_lt_i32_e32 vcc, v218, v212
	v_max3_f32 v0, v0, v186, v189
	s_nop 0
	v_cndmask_b32_e32 v186, v211, v218, vcc
	v_lshlrev_b32_e32 v186, 2, v186
	ds_bpermute_b32 v186, v186, v0
	s_waitcnt lgkmcnt(0)
	v_max3_f32 v186, v188, v0, v186
	v_sub_f32_e32 v0, v188, v186
	v_exp_f32_e32 v0, v0
	v_cmp_gt_f32_e32 vcc, v186, v188
	s_cbranch_vccz .LBB0_1999
	v_mul_f32_e32 v64, v64, v0
	v_mul_f32_e32 v65, v65, v0
	v_mul_f32_e32 v62, v62, v0
	v_mul_f32_e32 v63, v63, v0
	v_mul_f32_e32 v60, v60, v0
	v_mul_f32_e32 v61, v61, v0
	v_mul_f32_e32 v58, v58, v0
	v_mul_f32_e32 v59, v59, v0
	v_mul_f32_e32 v56, v56, v0
	v_mul_f32_e32 v57, v57, v0
	v_mul_f32_e32 v54, v54, v0
	v_mul_f32_e32 v55, v55, v0
	v_mul_f32_e32 v52, v52, v0
	v_mul_f32_e32 v53, v53, v0
	v_mul_f32_e32 v50, v50, v0
	v_mul_f32_e32 v51, v51, v0
	v_mul_f32_e32 v48, v48, v0
	v_mul_f32_e32 v49, v49, v0
	v_mul_f32_e32 v46, v46, v0
	v_mul_f32_e32 v47, v47, v0
	v_mul_f32_e32 v44, v44, v0
	v_mul_f32_e32 v45, v45, v0
	v_mul_f32_e32 v42, v42, v0
	v_mul_f32_e32 v43, v43, v0
	v_mul_f32_e32 v40, v40, v0
	v_mul_f32_e32 v41, v41, v0
	v_mul_f32_e32 v38, v38, v0
	v_mul_f32_e32 v39, v39, v0
	v_mul_f32_e32 v36, v36, v0
	v_mul_f32_e32 v37, v37, v0
	v_mul_f32_e32 v34, v34, v0
	v_mul_f32_e32 v35, v35, v0
	v_mul_f32_e32 v32, v32, v0
	v_mul_f32_e32 v33, v33, v0
	v_mul_f32_e32 v30, v30, v0
	v_mul_f32_e32 v31, v31, v0
	v_mul_f32_e32 v28, v28, v0
	v_mul_f32_e32 v29, v29, v0
	v_mul_f32_e32 v26, v26, v0
	v_mul_f32_e32 v27, v27, v0
	v_mul_f32_e32 v24, v24, v0
	v_mul_f32_e32 v25, v25, v0
	v_mul_f32_e32 v22, v22, v0
	v_mul_f32_e32 v23, v23, v0
	v_mul_f32_e32 v20, v20, v0
	v_mul_f32_e32 v21, v21, v0
	v_mul_f32_e32 v18, v18, v0
	v_mul_f32_e32 v19, v19, v0
	v_mul_f32_e32 v16, v16, v0
	v_mul_f32_e32 v17, v17, v0
	v_mul_f32_e32 v14, v14, v0
	v_mul_f32_e32 v15, v15, v0
	v_mul_f32_e32 v12, v12, v0
	v_mul_f32_e32 v13, v13, v0
	v_mul_f32_e32 v10, v10, v0
	v_mul_f32_e32 v11, v11, v0
	v_mul_f32_e32 v8, v8, v0
	v_mul_f32_e32 v9, v9, v0
	v_mul_f32_e32 v6, v6, v0
	v_mul_f32_e32 v7, v7, v0
	v_mul_f32_e32 v4, v4, v0
	v_mul_f32_e32 v5, v5, v0
	v_mul_f32_e32 v2, v2, v0
	v_mul_f32_e32 v3, v3, v0
